# attention: v15 relayout + two independent row-sum add chains
# speedup vs baseline: 1.0011x; 1.0011x over previous
.Latt_prio_done:
.LBB0_674:
	s_add_i32 s2, s67, -1
	s_and_b32 s2, s2, 3
	s_mulk_i32 s2, 0x3400
	s_and_b32 s71, s67, 2
	s_add_i32 s2, s2, 0
	s_xor_b32 s3, s71, 2
	v_add_u32_e32 v0, s2, v192
	s_mulk_i32 s3, 0x2400
	s_waitcnt vmcnt(5)
	ds_write_b128 v0, v[152:155]
	v_add_u32_e32 v0, s2, v185
	s_add_i32 s2, s67, 5
	s_waitcnt vmcnt(4)
	ds_write_b128 v0, v[156:159] offset:128
	v_add_u32_e32 v0, s3, v193
	s_min_i32 s46, s2, s66
	s_add_i32 s2, s67, 4
	v_add_u32_e32 v0, 0xd000, v0
	s_min_i32 s2, s2, s66
	s_lshl_b64 s[4:5], s[46:47], 16
	s_mov_b32 s3, s47
	s_waitcnt vmcnt(3)
	ds_write2_b64 v0, v[172:173], v[174:175] offset1:2
	v_lshl_add_u64 v[2:3], v[186:187], 0, s[4:5]
	s_lshl_b64 s[4:5], s[46:47], 12
	s_lshl_b64 s[2:3], s[2:3], 7
	v_lshl_add_u64 v[4:5], v[188:189], 0, s[4:5]
	global_load_dwordx4 v[152:155], v[2:3], off
	global_load_dwordx4 v[156:159], v[4:5], off
	v_lshl_add_u64 v[2:3], v[190:191], 0, s[2:3]
	global_load_dwordx4 v[172:175], v[2:3], off
	s_add_i32 s70, s67, 1
	s_and_b32 s69, s70, 3
	s_cmp_gt_i32 s67, s65
	s_cbranch_scc1 .LBB0_685
	s_mul_i32 s2, s69, 0x3400
	v_add_u32_e32 v0, s2, v196
	ds_read_b128 v[2:5], v0
	ds_read_b128 v[6:9], v0 offset:6656
	s_waitcnt lgkmcnt(1)
	v_mfma_f32_32x32x16_bf16 v[112:127], v[2:5], v[128:131], v[48:63]
	ds_read_b128 v[10:13], v0 offset:32
	ds_read_b128 v[202:205], v0 offset:6688
	v_add_f32_e32 v211, 0, v80
	v_add_f32_e32 v210, 0, v81
	v_cvt_pk_bf16_f32 v176, v80, v81
	s_waitcnt lgkmcnt(2)
	v_mfma_f32_32x32x16_bf16 v[96:111], v[6:9], v[128:131], v[48:63]
	v_add_f32_e32 v211, v82, v211
	v_add_f32_e32 v210, v83, v210
	v_add_f32_e32 v211, v84, v211
	v_cvt_pk_bf16_f32 v177, v82, v83
	s_waitcnt lgkmcnt(1)
	v_mfma_f32_32x32x16_bf16 v[112:127], v[10:13], v[132:135], v[112:127]
	ds_read_b128 v[2:5], v0 offset:64
	ds_read_b128 v[6:9], v0 offset:6720
	v_add_f32_e32 v210, v85, v210
	v_add_f32_e32 v211, v86, v211
	v_add_f32_e32 v210, v87, v210
	v_cvt_pk_bf16_f32 v178, v84, v85
	v_cvt_pk_bf16_f32 v179, v86, v87
	s_waitcnt lgkmcnt(2)
	v_mfma_f32_32x32x16_bf16 v[96:111], v[202:205], v[132:135], v[96:111]
	v_add_f32_e32 v211, v88, v211
	v_add_f32_e32 v210, v89, v210
	v_cvt_pk_bf16_f32 v10, v88, v89
	s_waitcnt lgkmcnt(1)
	v_mfma_f32_32x32x16_bf16 v[112:127], v[2:5], v[136:139], v[112:127]
	ds_read_b128 v[80:83], v0 offset:96
	ds_read_b128 v[202:205], v0 offset:6752
	v_add_f32_e32 v211, v90, v211
	v_add_f32_e32 v210, v91, v210
	v_add_f32_e32 v211, v92, v211
	v_cvt_pk_bf16_f32 v11, v90, v91
	s_waitcnt lgkmcnt(2)
	v_mfma_f32_32x32x16_bf16 v[96:111], v[6:9], v[136:139], v[96:111]
	v_add_f32_e32 v210, v93, v210
	v_add_f32_e32 v211, v94, v211
	v_add_f32_e32 v210, v95, v210
	v_cvt_pk_bf16_f32 v12, v92, v93
	v_cvt_pk_bf16_f32 v13, v94, v95
	s_waitcnt lgkmcnt(1)
	v_mfma_f32_32x32x16_bf16 v[112:127], v[80:83], v[140:143], v[112:127]
	ds_read_b128 v[2:5], v0 offset:128
	ds_read_b128 v[206:209], v0 offset:6784
	v_add_f32_e32 v211, v16, v211
	v_add_f32_e32 v210, v17, v210
	v_cvt_pk_bf16_f32 v6, v16, v17
	s_waitcnt lgkmcnt(2)
	v_mfma_f32_32x32x16_bf16 v[96:111], v[202:205], v[140:143], v[96:111]
	v_add_f32_e32 v211, v18, v211
	v_add_f32_e32 v210, v19, v210
	v_add_f32_e32 v211, v20, v211
	v_cvt_pk_bf16_f32 v7, v18, v19
	s_waitcnt lgkmcnt(1)
	v_mfma_f32_32x32x16_bf16 v[112:127], v[2:5], v[144:147], v[112:127]
	ds_read_b128 v[14:17], v0 offset:160
	ds_read_b128 v[80:83], v0 offset:6816
	v_add_f32_e32 v210, v21, v210
	v_add_f32_e32 v211, v22, v211
	v_add_f32_e32 v210, v23, v210
	v_cvt_pk_bf16_f32 v8, v20, v21
	v_cvt_pk_bf16_f32 v9, v22, v23
	s_waitcnt lgkmcnt(2)
	v_mfma_f32_32x32x16_bf16 v[96:111], v[206:209], v[144:147], v[96:111]
	v_add_f32_e32 v211, v24, v211
	v_add_f32_e32 v210, v25, v210
	v_cvt_pk_bf16_f32 v2, v24, v25
	s_waitcnt lgkmcnt(1)
	v_mfma_f32_32x32x16_bf16 v[112:127], v[14:17], v[148:151], v[112:127]
	v_add_f32_e32 v211, v26, v211
	v_add_f32_e32 v210, v27, v210
	v_add_f32_e32 v211, v28, v211
	v_cvt_pk_bf16_f32 v3, v26, v27
	s_waitcnt lgkmcnt(0)
	v_mfma_f32_32x32x16_bf16 v[96:111], v[80:83], v[148:151], v[96:111]
	v_add_f32_e32 v210, v29, v210
	v_add_f32_e32 v211, v30, v211
	v_add_f32_e32 v210, v31, v210
	v_add_f32_e32 v0, v210, v211
	v_cvt_pk_bf16_f32 v4, v28, v29
	v_cvt_pk_bf16_f32 v5, v30, v31
	s_mul_i32 s4, s71, 0x2400
	v_add_u32_e32 v206, s4, v200
	ds_read_b128 v[16:19], v206 offset:53248
	ds_read_b128 v[202:205], v206 offset:57856
	s_cmp_ge_i32 s67, s65
	v_add_f32_e32 v201, v201, v0
	s_cbranch_scc1 .LBB0_682
	s_sub_i32 s2, s68, 64
	s_cmp_le_i32 s2, s63
	s_cbranch_scc0 .Latt_mask0

.LBB0_685:
	s_mulk_i32 s71, 0x3400
	s_add_i32 s3, s71, 0
	s_xor_b32 s2, s69, 2
	v_add_u32_e32 v0, s3, v192
	s_mulk_i32 s2, 0x2400
	s_waitcnt vmcnt(5)
	ds_write_b128 v0, v[168:171]
	v_add_u32_e32 v0, s3, v185
	s_waitcnt vmcnt(4)
	ds_write_b128 v0, v[164:167] offset:128
	v_add_u32_e32 v0, s2, v193
	s_add_i32 s2, s67, 6
	s_min_i32 s2, s2, s66
	s_mov_b32 s3, s47
	v_add_u32_e32 v0, 0xd000, v0
	s_lshl_b64 s[4:5], s[2:3], 16
	s_lshl_b64 s[2:3], s[2:3], 12
	s_waitcnt vmcnt(3)
	ds_write2_b64 v0, v[160:161], v[162:163] offset1:2
	v_lshl_add_u64 v[2:3], v[186:187], 0, s[4:5]
	v_lshl_add_u64 v[4:5], v[188:189], 0, s[2:3]
	s_lshl_b64 s[2:3], s[46:47], 7
	global_load_dwordx4 v[168:171], v[2:3], off
	global_load_dwordx4 v[164:167], v[4:5], off
	v_lshl_add_u64 v[2:3], v[190:191], 0, s[2:3]
	global_load_dwordx4 v[160:163], v[2:3], off
	s_add_i32 s46, s67, 2
	s_cmp_ge_i32 s67, s65
	s_cbranch_scc1 .LBB0_696
	s_and_b32 s2, s46, 2
	s_mulk_i32 s2, 0x3400
	v_add_u32_e32 v0, s2, v196
	ds_read_b128 v[2:5], v0
	ds_read_b128 v[6:9], v0 offset:6656
	s_waitcnt lgkmcnt(1)
	v_mfma_f32_32x32x16_bf16 v[112:127], v[2:5], v[128:131], v[48:63]
	ds_read_b128 v[10:13], v0 offset:32
	ds_read_b128 v[202:205], v0 offset:6688
	v_add_f32_e32 v211, 0, v80
	v_add_f32_e32 v210, 0, v81
	v_cvt_pk_bf16_f32 v176, v80, v81
	s_waitcnt lgkmcnt(2)
	v_mfma_f32_32x32x16_bf16 v[96:111], v[6:9], v[128:131], v[48:63]
	v_add_f32_e32 v211, v82, v211
	v_add_f32_e32 v210, v83, v210
	v_add_f32_e32 v211, v84, v211
	v_cvt_pk_bf16_f32 v177, v82, v83
	s_waitcnt lgkmcnt(1)
	v_mfma_f32_32x32x16_bf16 v[112:127], v[10:13], v[132:135], v[112:127]
	ds_read_b128 v[2:5], v0 offset:64
	ds_read_b128 v[6:9], v0 offset:6720
	v_add_f32_e32 v210, v85, v210
	v_add_f32_e32 v211, v86, v211
	v_add_f32_e32 v210, v87, v210
	v_cvt_pk_bf16_f32 v178, v84, v85
	v_cvt_pk_bf16_f32 v179, v86, v87
	s_waitcnt lgkmcnt(2)
	v_mfma_f32_32x32x16_bf16 v[96:111], v[202:205], v[132:135], v[96:111]
	v_add_f32_e32 v211, v88, v211
	v_add_f32_e32 v210, v89, v210
	v_cvt_pk_bf16_f32 v10, v88, v89
	s_waitcnt lgkmcnt(1)
	v_mfma_f32_32x32x16_bf16 v[112:127], v[2:5], v[136:139], v[112:127]
	ds_read_b128 v[80:83], v0 offset:96
	ds_read_b128 v[202:205], v0 offset:6752
	v_add_f32_e32 v211, v90, v211
	v_add_f32_e32 v210, v91, v210
	v_add_f32_e32 v211, v92, v211
	v_cvt_pk_bf16_f32 v11, v90, v91
	s_waitcnt lgkmcnt(2)
	v_mfma_f32_32x32x16_bf16 v[96:111], v[6:9], v[136:139], v[96:111]
	v_add_f32_e32 v210, v93, v210
	v_add_f32_e32 v211, v94, v211
	v_add_f32_e32 v210, v95, v210
	v_cvt_pk_bf16_f32 v12, v92, v93
	v_cvt_pk_bf16_f32 v13, v94, v95
	s_waitcnt lgkmcnt(1)
	v_mfma_f32_32x32x16_bf16 v[112:127], v[80:83], v[140:143], v[112:127]
	ds_read_b128 v[2:5], v0 offset:128
	ds_read_b128 v[206:209], v0 offset:6784
	v_add_f32_e32 v211, v16, v211
	v_add_f32_e32 v210, v17, v210
	v_cvt_pk_bf16_f32 v6, v16, v17
	s_waitcnt lgkmcnt(2)
	v_mfma_f32_32x32x16_bf16 v[96:111], v[202:205], v[140:143], v[96:111]
	v_add_f32_e32 v211, v18, v211
	v_add_f32_e32 v210, v19, v210
	v_add_f32_e32 v211, v20, v211
	v_cvt_pk_bf16_f32 v7, v18, v19
	s_waitcnt lgkmcnt(1)
	v_mfma_f32_32x32x16_bf16 v[112:127], v[2:5], v[144:147], v[112:127]
	ds_read_b128 v[14:17], v0 offset:160
	ds_read_b128 v[80:83], v0 offset:6816
	v_add_f32_e32 v210, v21, v210
	v_add_f32_e32 v211, v22, v211
	v_add_f32_e32 v210, v23, v210
	v_cvt_pk_bf16_f32 v8, v20, v21
	v_cvt_pk_bf16_f32 v9, v22, v23
	s_waitcnt lgkmcnt(2)
	v_mfma_f32_32x32x16_bf16 v[96:111], v[206:209], v[144:147], v[96:111]
	v_add_f32_e32 v211, v24, v211
	v_add_f32_e32 v210, v25, v210
	v_cvt_pk_bf16_f32 v2, v24, v25
	s_waitcnt lgkmcnt(1)
	v_mfma_f32_32x32x16_bf16 v[112:127], v[14:17], v[148:151], v[112:127]
	v_add_f32_e32 v211, v26, v211
	v_add_f32_e32 v210, v27, v210
	v_add_f32_e32 v211, v28, v211
	v_cvt_pk_bf16_f32 v3, v26, v27
	s_waitcnt lgkmcnt(0)
	v_mfma_f32_32x32x16_bf16 v[96:111], v[80:83], v[148:151], v[96:111]
	v_add_f32_e32 v210, v29, v210
	v_add_f32_e32 v211, v30, v211
	v_add_f32_e32 v210, v31, v210
	v_add_f32_e32 v0, v210, v211
	v_cvt_pk_bf16_f32 v4, v28, v29
	v_cvt_pk_bf16_f32 v5, v30, v31
	s_mul_i32 s4, s69, 0x2400
	v_add_u32_e32 v206, s4, v200
	ds_read_b128 v[16:19], v206 offset:53248
	ds_read_b128 v[202:205], v206 offset:57856
	s_cmp_ge_i32 s70, s65
	v_add_f32_e32 v201, v201, v0
	s_cbranch_scc1 .LBB0_693
	s_cmp_le_i32 s68, s63
	s_cbranch_scc0 .Latt_mask1
